# P5 row loop processes two items per trip with both items' loads in flight (renamed second register set)
# speedup vs baseline: 1.0067x; 1.0023x over previous
.LBB0_1613:
	v_readfirstlane_b32 s84, v3
	s_nop 0
	s_add_i32 s84, s84, s12
	s_cmp_gt_i32 s84, s14
	s_cbranch_scc1 .Lp5_single
	s_waitcnt vmcnt(6)
	v_ashrrev_i32_e32 v26, 1, v3
	v_ashrrev_i32_e32 v27, 31, v26
	v_lshlrev_b64 v[28:29], 11, v[26:27]
	v_lshlrev_b64 v[26:27], 6, v[26:27]
	v_lshl_or_b32 v28, v2, 1, v28
	s_waitcnt vmcnt(4)
	v_lshl_add_u64 v[38:39], v[4:5], 0, v[26:27]
	v_lshl_add_u64 v[40:41], s[4:5], 0, v[28:29]
	v_lshl_add_u64 v[30:31], s[6:7], 0, v[28:29]
	v_lshl_add_u64 v[34:35], s[8:9], 0, v[28:29]
	global_load_dwordx4 v[10:13], v[6:7], off offset:16
	global_load_dwordx4 v[14:17], v[6:7], off
	global_load_dwordx4 v[18:21], v[8:9], off offset:16
	global_load_dwordx4 v[22:25], v[8:9], off
	global_load_dwordx4 v[26:29], v[40:41], off
	s_nop 0
	global_load_dwordx4 v[30:33], v[30:31], off
	s_nop 0
	global_load_dwordx4 v[34:37], v[34:35], off
	s_nop 0
	global_load_dword v38, v[38:39], off
	v_add_u32_e32 v126, s12, v3
	v_ashrrev_i32_e32 v90, 1, v126
	v_ashrrev_i32_e32 v91, 31, v90
	v_lshlrev_b64 v[92:93], 11, v[90:91]
	v_lshlrev_b64 v[90:91], 6, v[90:91]
	v_lshl_or_b32 v92, v2, 1, v92
	v_lshl_add_u64 v[102:103], v[4:5], 0, v[90:91]
	v_lshl_add_u64 v[104:105], s[4:5], 0, v[92:93]
	v_lshl_add_u64 v[94:95], s[6:7], 0, v[92:93]
	v_lshl_add_u64 v[98:99], s[8:9], 0, v[92:93]
	global_load_dwordx4 v[74:77], v[6:7], off offset:16
	global_load_dwordx4 v[78:81], v[6:7], off
	global_load_dwordx4 v[82:85], v[8:9], off offset:16
	global_load_dwordx4 v[86:89], v[8:9], off
	global_load_dwordx4 v[90:93], v[104:105], off
	s_nop 0
	global_load_dwordx4 v[94:97], v[94:95], off
	s_nop 0
	global_load_dwordx4 v[98:101], v[98:99], off
	s_nop 0
	global_load_dword v102, v[102:103], off
	v_add_u32_e32 v3, s12, v126
	v_cmp_lt_i32_e32 vcc, s14, v3
	s_or_b64 s[10:11], vcc, s[10:11]
	s_waitcnt vmcnt(11)
	v_lshlrev_b32_e32 v42, 16, v26
	v_and_b32_e32 v43, 0xffff0000, v26
	v_add_f32_e32 v39, 0, v42
	v_lshlrev_b32_e32 v26, 16, v27
	v_add_f32_e32 v39, v39, v43
	v_and_b32_e32 v27, 0xffff0000, v27
	v_add_f32_e32 v39, v39, v26
	v_lshlrev_b32_e32 v44, 16, v28
	v_add_f32_e32 v39, v39, v27
	v_and_b32_e32 v45, 0xffff0000, v28
	v_add_f32_e32 v39, v39, v44
	v_lshlrev_b32_e32 v28, 16, v29
	v_add_f32_e32 v39, v39, v45
	v_and_b32_e32 v29, 0xffff0000, v29
	v_add_f32_e32 v39, v39, v28
	v_add_f32_e32 v39, v39, v29
	s_waitcnt vmcnt(10)
	v_lshlrev_b32_e32 v46, 16, v30
	v_and_b32_e32 v47, 0xffff0000, v30
	v_add_f32_dpp v39, v39, v39 quad_perm:[1,0,3,2] row_mask:0xf bank_mask:0xf bound_ctrl:1
	v_lshlrev_b32_e32 v30, 16, v31
	v_and_b32_e32 v31, 0xffff0000, v31
	v_add_f32_dpp v39, v39, v39 quad_perm:[2,3,0,1] row_mask:0xf bank_mask:0xf bound_ctrl:1
	v_lshlrev_b32_e32 v48, 16, v32
	v_and_b32_e32 v49, 0xffff0000, v32
	v_add_f32_dpp v39, v39, v39 row_half_mirror row_mask:0xf bank_mask:0xf bound_ctrl:1
	v_mul_f32_e32 v54, 0x3c800000, v39
	v_pk_add_f32 v[42:43], v[42:43], v[54:55] op_sel_hi:[1,0] neg_lo:[0,1] neg_hi:[0,1]
	v_pk_add_f32 v[26:27], v[26:27], v[54:55] op_sel_hi:[1,0] neg_lo:[0,1] neg_hi:[0,1]
	v_pk_add_f32 v[44:45], v[44:45], v[54:55] op_sel_hi:[1,0] neg_lo:[0,1] neg_hi:[0,1]
	v_pk_add_f32 v[28:29], v[28:29], v[54:55] op_sel_hi:[1,0] neg_lo:[0,1] neg_hi:[0,1]
	v_pk_mul_f32 v[54:55], v[42:43], v[42:43]
	v_pk_mul_f32 v[56:57], v[26:27], v[26:27]
	v_add_f32_e32 v39, v54, v55
	v_add_f32_e32 v39, v56, v39
	v_pk_mul_f32 v[58:59], v[44:45], v[44:45]
	v_add_f32_e32 v39, v57, v39
	v_add_f32_e32 v39, v58, v39
	v_pk_mul_f32 v[60:61], v[28:29], v[28:29]
	v_add_f32_e32 v39, v59, v39
	v_add_f32_e32 v39, v60, v39
	v_add_f32_e32 v39, v61, v39
	v_lshlrev_b32_e32 v32, 16, v33
	v_and_b32_e32 v33, 0xffff0000, v33
	v_add_f32_dpp v39, v39, v39 quad_perm:[1,0,3,2] row_mask:0xf bank_mask:0xf bound_ctrl:1
	s_waitcnt vmcnt(9)
	v_lshlrev_b32_e32 v50, 16, v34
	v_and_b32_e32 v51, 0xffff0000, v34
	v_add_f32_dpp v39, v39, v39 quad_perm:[2,3,0,1] row_mask:0xf bank_mask:0xf bound_ctrl:1
	v_lshlrev_b32_e32 v34, 16, v35
	v_and_b32_e32 v35, 0xffff0000, v35
	v_add_f32_dpp v39, v39, v39 row_half_mirror row_mask:0xf bank_mask:0xf bound_ctrl:1
	v_fmamk_f32 v39, v39, 0x3c800000, v1
	v_mul_f32_e32 v54, 0x4b800000, v39
	v_cmp_gt_f32_e32 vcc, s13, v39
	v_lshlrev_b32_e32 v52, 16, v36
	v_and_b32_e32 v53, 0xffff0000, v36
	v_cndmask_b32_e32 v39, v39, v54, vcc
	v_rsq_f32_e32 v39, v39
	v_lshlrev_b32_e32 v36, 16, v37
	v_and_b32_e32 v37, 0xffff0000, v37
	v_mul_f32_e32 v54, 0x45800000, v39
	v_cndmask_b32_e32 v54, v39, v54, vcc
	v_pk_mul_f32 v[42:43], v[42:43], v[54:55] op_sel_hi:[1,0]
	v_pk_mul_f32 v[26:27], v[26:27], v[54:55] op_sel_hi:[1,0]
	v_pk_mul_f32 v[44:45], v[44:45], v[54:55] op_sel_hi:[1,0]
	v_pk_mul_f32 v[28:29], v[28:29], v[54:55] op_sel_hi:[1,0]
	v_pk_fma_f32 v[14:15], v[14:15], v[42:43], v[22:23]
	v_pk_fma_f32 v[16:17], v[16:17], v[26:27], v[24:25]
	v_pk_fma_f32 v[10:11], v[10:11], v[44:45], v[18:19]
	v_pk_fma_f32 v[12:13], v[12:13], v[28:29], v[20:21]
	s_waitcnt vmcnt(8)
	v_pk_fma_f32 v[14:15], v[38:39], v[46:47], v[14:15] op_sel_hi:[0,1,1]
	v_pk_fma_f32 v[16:17], v[38:39], v[30:31], v[16:17] op_sel_hi:[0,1,1]
	v_pk_fma_f32 v[10:11], v[38:39], v[48:49], v[10:11] op_sel_hi:[0,1,1]
	v_pk_fma_f32 v[12:13], v[38:39], v[32:33], v[12:13] op_sel_hi:[0,1,1]
	v_pk_mul_f32 v[14:15], v[14:15], v[50:51]
	v_pk_mul_f32 v[16:17], v[16:17], v[34:35]
	v_pk_mul_f32 v[18:19], v[10:11], v[52:53]
	v_pk_mul_f32 v[20:21], v[12:13], v[36:37]
	v_cvt_pk_bf16_f32 v10, v14, v15
	v_cvt_pk_bf16_f32 v11, v16, v17
	v_cvt_pk_bf16_f32 v12, v18, v19
	v_cvt_pk_bf16_f32 v13, v20, v21
	global_store_dwordx4 v[40:41], v[10:13], off
	s_waitcnt vmcnt(4)
	v_lshlrev_b32_e32 v106, 16, v90
	v_and_b32_e32 v107, 0xffff0000, v90
	v_add_f32_e32 v103, 0, v106
	v_lshlrev_b32_e32 v90, 16, v91
	v_add_f32_e32 v103, v103, v107
	v_and_b32_e32 v91, 0xffff0000, v91
	v_add_f32_e32 v103, v103, v90
	v_lshlrev_b32_e32 v108, 16, v92
	v_add_f32_e32 v103, v103, v91
	v_and_b32_e32 v109, 0xffff0000, v92
	v_add_f32_e32 v103, v103, v108
	v_lshlrev_b32_e32 v92, 16, v93
	v_add_f32_e32 v103, v103, v109
	v_and_b32_e32 v93, 0xffff0000, v93
	v_add_f32_e32 v103, v103, v92
	v_add_f32_e32 v103, v103, v93
	s_waitcnt vmcnt(3)
	v_lshlrev_b32_e32 v110, 16, v94
	v_and_b32_e32 v111, 0xffff0000, v94
	v_add_f32_dpp v103, v103, v103 quad_perm:[1,0,3,2] row_mask:0xf bank_mask:0xf bound_ctrl:1
	v_lshlrev_b32_e32 v94, 16, v95
	v_and_b32_e32 v95, 0xffff0000, v95
	v_add_f32_dpp v103, v103, v103 quad_perm:[2,3,0,1] row_mask:0xf bank_mask:0xf bound_ctrl:1
	v_lshlrev_b32_e32 v112, 16, v96
	v_and_b32_e32 v113, 0xffff0000, v96
	v_add_f32_dpp v103, v103, v103 row_half_mirror row_mask:0xf bank_mask:0xf bound_ctrl:1
	v_mul_f32_e32 v118, 0x3c800000, v103
	v_pk_add_f32 v[106:107], v[106:107], v[118:119] op_sel_hi:[1,0] neg_lo:[0,1] neg_hi:[0,1]
	v_pk_add_f32 v[90:91], v[90:91], v[118:119] op_sel_hi:[1,0] neg_lo:[0,1] neg_hi:[0,1]
	v_pk_add_f32 v[108:109], v[108:109], v[118:119] op_sel_hi:[1,0] neg_lo:[0,1] neg_hi:[0,1]
	v_pk_add_f32 v[92:93], v[92:93], v[118:119] op_sel_hi:[1,0] neg_lo:[0,1] neg_hi:[0,1]
	v_pk_mul_f32 v[118:119], v[106:107], v[106:107]
	v_pk_mul_f32 v[120:121], v[90:91], v[90:91]
	v_add_f32_e32 v103, v118, v119
	v_add_f32_e32 v103, v120, v103
	v_pk_mul_f32 v[122:123], v[108:109], v[108:109]
	v_add_f32_e32 v103, v121, v103
	v_add_f32_e32 v103, v122, v103
	v_pk_mul_f32 v[124:125], v[92:93], v[92:93]
	v_add_f32_e32 v103, v123, v103
	v_add_f32_e32 v103, v124, v103
	v_add_f32_e32 v103, v125, v103
	v_lshlrev_b32_e32 v96, 16, v97
	v_and_b32_e32 v97, 0xffff0000, v97
	v_add_f32_dpp v103, v103, v103 quad_perm:[1,0,3,2] row_mask:0xf bank_mask:0xf bound_ctrl:1
	s_waitcnt vmcnt(2)
	v_lshlrev_b32_e32 v114, 16, v98
	v_and_b32_e32 v115, 0xffff0000, v98
	v_add_f32_dpp v103, v103, v103 quad_perm:[2,3,0,1] row_mask:0xf bank_mask:0xf bound_ctrl:1
	v_lshlrev_b32_e32 v98, 16, v99
	v_and_b32_e32 v99, 0xffff0000, v99
	v_add_f32_dpp v103, v103, v103 row_half_mirror row_mask:0xf bank_mask:0xf bound_ctrl:1
	v_fmamk_f32 v103, v103, 0x3c800000, v1
	v_mul_f32_e32 v118, 0x4b800000, v103
	v_cmp_gt_f32_e32 vcc, s13, v103
	v_lshlrev_b32_e32 v116, 16, v100
	v_and_b32_e32 v117, 0xffff0000, v100
	v_cndmask_b32_e32 v103, v103, v118, vcc
	v_rsq_f32_e32 v103, v103
	v_lshlrev_b32_e32 v100, 16, v101
	v_and_b32_e32 v101, 0xffff0000, v101
	v_mul_f32_e32 v118, 0x45800000, v103
	v_cndmask_b32_e32 v118, v103, v118, vcc
	v_pk_mul_f32 v[106:107], v[106:107], v[118:119] op_sel_hi:[1,0]
	v_pk_mul_f32 v[90:91], v[90:91], v[118:119] op_sel_hi:[1,0]
	v_pk_mul_f32 v[108:109], v[108:109], v[118:119] op_sel_hi:[1,0]
	v_pk_mul_f32 v[92:93], v[92:93], v[118:119] op_sel_hi:[1,0]
	v_pk_fma_f32 v[78:79], v[78:79], v[106:107], v[86:87]
	v_pk_fma_f32 v[80:81], v[80:81], v[90:91], v[88:89]
	v_pk_fma_f32 v[74:75], v[74:75], v[108:109], v[82:83]
	v_pk_fma_f32 v[76:77], v[76:77], v[92:93], v[84:85]
	s_waitcnt vmcnt(1)
	v_pk_fma_f32 v[78:79], v[102:103], v[110:111], v[78:79] op_sel_hi:[0,1,1]
	v_pk_fma_f32 v[80:81], v[102:103], v[94:95], v[80:81] op_sel_hi:[0,1,1]
	v_pk_fma_f32 v[74:75], v[102:103], v[112:113], v[74:75] op_sel_hi:[0,1,1]
	v_pk_fma_f32 v[76:77], v[102:103], v[96:97], v[76:77] op_sel_hi:[0,1,1]
	v_pk_mul_f32 v[78:79], v[78:79], v[114:115]
	v_pk_mul_f32 v[80:81], v[80:81], v[98:99]
	v_pk_mul_f32 v[82:83], v[74:75], v[116:117]
	v_pk_mul_f32 v[84:85], v[76:77], v[100:101]
	v_cvt_pk_bf16_f32 v74, v78, v79
	v_cvt_pk_bf16_f32 v75, v80, v81
	v_cvt_pk_bf16_f32 v76, v82, v83
	v_cvt_pk_bf16_f32 v77, v84, v85
	global_store_dwordx4 v[104:105], v[74:77], off
	s_andn2_b64 exec, exec, s[10:11]
	s_cbranch_execnz .LBB0_1613
	s_branch .LBB0_1614
